# P13 final-norm loop rewritten: all row loads issued together, next row prefetched
# speedup vs baseline: 1.0096x; 1.0096x over previous
.LBB0_1399:
	s_cmp_lt_i32 s58, 14
	s_cselect_b64 s[2:3], -1, 0
	s_and_b64 s[0:1], s[2:3], s[0:1]
	s_cmp_lt_i32 s28, 0x8000
	s_cselect_b64 s[2:3], -1, 0
	s_and_b64 s[0:1], s[0:1], s[2:3]
	s_andn2_b64 vcc, exec, s[0:1]
	s_cbranch_vccnz .LBB0_1402
	s_ashr_i32 s29, s28, 31
	s_ashr_i32 s95, s94, 31
	s_lshl_b64 s[0:1], s[28:29], 6
	s_add_u32 s0, s0, s56
	s_addc_u32 s1, s1, s57
	s_add_u32 s0, s0, 0xa00000
	s_addc_u32 s1, s1, 0
	s_lshl_b64 s[2:3], s[28:29], 11
	s_add_u32 s2, s2, s56
	s_addc_u32 s3, s3, s57
	s_add_u32 s2, s2, 0x4200000
	s_addc_u32 s3, s3, 0
	s_lshl_b64 s[4:5], s[28:29], 12
	s_add_u32 s4, s4, s54
	s_addc_u32 s5, s5, s55
	s_lshl_b64 s[6:7], s[94:95], 6
	s_lshl_b64 s[8:9], s[94:95], 11
	s_lshl_b64 s[12:13], s[94:95], 12
	v_lshlrev_b32_e32 v1, 3, v190
	v_lshlrev_b32_e32 v2, 4, v190
	v_mov_b32_e32 v3, 0
	s_waitcnt lgkmcnt(0)
	global_load_dwordx4 v[56:59], v3, s[0:1]
	global_load_dwordx4 v[60:63], v3, s[0:1] offset:16
	global_load_dwordx4 v[64:67], v3, s[0:1] offset:32
	global_load_dwordx4 v[68:71], v3, s[0:1] offset:48
	global_load_dwordx2 v[72:73], v1, s[2:3]
	global_load_dwordx2 v[74:75], v1, s[2:3] offset:512
	global_load_dwordx2 v[76:77], v1, s[2:3] offset:1024
	global_load_dwordx2 v[78:79], v1, s[2:3] offset:1536
	global_load_dwordx4 v[40:43], v2, s[52:53]
	global_load_dwordx4 v[44:47], v2, s[52:53] offset:1024
	global_load_dwordx4 v[48:51], v2, s[52:53] offset:2048
	global_load_dwordx4 v[52:55], v2, s[52:53] offset:3072
	v_mov_b32_e32 v8, 0x358637bd
	s_mov_b32 s10, 0xf800000
	v_mov_b32_e32 v9, 0x260
.Lp13_loop:
	s_waitcnt vmcnt(4)
	v_add_f32_e32 v10, v56, v57
	v_add_f32_e32 v11, v58, v59
	v_add_f32_e32 v12, v60, v61
	v_add_f32_e32 v13, v62, v63
	v_add_f32_e32 v16, v64, v65
	v_add_f32_e32 v17, v66, v67
	v_add_f32_e32 v18, v68, v69
	v_add_f32_e32 v19, v70, v71
	v_add_f32_e32 v10, v10, v11
	v_add_f32_e32 v12, v12, v13
	v_add_f32_e32 v16, v16, v17
	v_add_f32_e32 v18, v18, v19
	v_add_f32_e32 v10, v10, v12
	v_add_f32_e32 v16, v16, v18
	v_add_f32_e32 v10, v10, v16
	v_lshlrev_b32_e32 v88, 16, v72
	v_and_b32_e32 v89, 0xffff0000, v72
	v_lshlrev_b32_e32 v90, 16, v73
	v_and_b32_e32 v91, 0xffff0000, v73
	v_lshlrev_b32_e32 v92, 16, v74
	v_and_b32_e32 v93, 0xffff0000, v74
	v_lshlrev_b32_e32 v94, 16, v75
	v_and_b32_e32 v95, 0xffff0000, v75
	v_lshlrev_b32_e32 v96, 16, v76
	v_and_b32_e32 v97, 0xffff0000, v76
	v_lshlrev_b32_e32 v98, 16, v77
	v_and_b32_e32 v99, 0xffff0000, v77
	v_lshlrev_b32_e32 v100, 16, v78
	v_and_b32_e32 v101, 0xffff0000, v78
	v_lshlrev_b32_e32 v102, 16, v79
	v_and_b32_e32 v103, 0xffff0000, v79
	s_add_i32 s28, s28, s94
	s_cmp_lt_i32 s28, 0x8000
	s_cselect_b32 s17, 1, 0
	s_cselect_b64 s[18:19], s[6:7], 0
	s_cselect_b64 s[20:21], s[8:9], 0
	s_add_u32 s0, s0, s18
	s_addc_u32 s1, s1, s19
	s_add_u32 s2, s2, s20
	s_addc_u32 s3, s3, s21
	global_load_dwordx4 v[56:59], v3, s[0:1]
	global_load_dwordx4 v[60:63], v3, s[0:1] offset:16
	global_load_dwordx4 v[64:67], v3, s[0:1] offset:32
	global_load_dwordx4 v[68:71], v3, s[0:1] offset:48
	global_load_dwordx2 v[72:73], v1, s[2:3]
	global_load_dwordx2 v[74:75], v1, s[2:3] offset:512
	global_load_dwordx2 v[76:77], v1, s[2:3] offset:1024
	global_load_dwordx2 v[78:79], v1, s[2:3] offset:1536
	v_fmamk_f32 v10, v10, 0x3a800000, v8
	v_mul_f32_e32 v11, 0x4f800000, v10
	v_cmp_gt_f32_e32 vcc, s10, v10
	s_nop 1
	v_cndmask_b32_e32 v10, v10, v11, vcc
	v_sqrt_f32_e32 v11, v10
	s_nop 0
	v_add_u32_e32 v14, -1, v11
	v_add_u32_e32 v15, 1, v11
	v_fma_f32 v16, -v14, v11, v10
	v_fma_f32 v17, -v15, v11, v10
	v_cmp_ge_f32_e64 s[22:23], 0, v16
	s_nop 1
	v_cndmask_b32_e64 v11, v11, v14, s[22:23]
	v_cmp_lt_f32_e64 s[22:23], 0, v17
	s_nop 1
	v_cndmask_b32_e64 v11, v11, v15, s[22:23]
	v_mul_f32_e32 v14, 0x37800000, v11
	v_cndmask_b32_e32 v11, v11, v14, vcc
	v_cmp_class_f32_e32 vcc, v10, v9
	s_nop 1
	v_cndmask_b32_e32 v10, v11, v10, vcc
	v_div_scale_f32 v11, s[22:23], v10, v10, 1.0
	v_rcp_f32_e32 v15, v11
	v_div_scale_f32 v14, vcc, 1.0, v10, 1.0
	v_fma_f32 v16, -v11, v15, 1.0
	v_fmac_f32_e32 v15, v16, v15
	v_mul_f32_e32 v16, v14, v15
	v_fma_f32 v17, -v11, v16, v14
	v_fmac_f32_e32 v16, v17, v15
	v_fma_f32 v11, -v11, v16, v14
	v_div_fmas_f32 v11, v11, v15, v16
	v_div_fixup_f32 v14, v11, v10, 1.0
	v_pk_mul_f32 v[88:89], v[14:15], v[88:89] op_sel_hi:[0,1]
	v_pk_mul_f32 v[90:91], v[14:15], v[90:91] op_sel_hi:[0,1]
	v_pk_mul_f32 v[92:93], v[14:15], v[92:93] op_sel_hi:[0,1]
	v_pk_mul_f32 v[94:95], v[14:15], v[94:95] op_sel_hi:[0,1]
	v_pk_mul_f32 v[96:97], v[14:15], v[96:97] op_sel_hi:[0,1]
	v_pk_mul_f32 v[98:99], v[14:15], v[98:99] op_sel_hi:[0,1]
	v_pk_mul_f32 v[100:101], v[14:15], v[100:101] op_sel_hi:[0,1]
	v_pk_mul_f32 v[102:103], v[14:15], v[102:103] op_sel_hi:[0,1]
	s_waitcnt vmcnt(8)
	v_pk_mul_f32 v[88:89], v[40:41], v[88:89]
	v_pk_mul_f32 v[90:91], v[42:43], v[90:91]
	v_pk_mul_f32 v[92:93], v[44:45], v[92:93]
	v_pk_mul_f32 v[94:95], v[46:47], v[94:95]
	v_pk_mul_f32 v[96:97], v[48:49], v[96:97]
	v_pk_mul_f32 v[98:99], v[50:51], v[98:99]
	v_pk_mul_f32 v[100:101], v[52:53], v[100:101]
	v_pk_mul_f32 v[102:103], v[54:55], v[102:103]
	global_store_dwordx4 v2, v[88:91], s[4:5]
	global_store_dwordx4 v2, v[92:95], s[4:5] offset:1024
	global_store_dwordx4 v2, v[96:99], s[4:5] offset:2048
	global_store_dwordx4 v2, v[100:103], s[4:5] offset:3072
	s_add_u32 s4, s4, s12
	s_addc_u32 s5, s5, s13
	s_cmp_lg_u32 s17, 0
	s_cbranch_scc1 .Lp13_loop
